# gather_u: segment code duplicated per prefetch buffer, dots read the double-buffered X/idx registers directly (no per-token copy)
# baseline (speedup 1.0000x reference)
; __device__ void phase_gather_u(const Params& p) {
;     ...
;     for (int t = tbase; t < T_TOK; t += tstride) {
;       const u32x4 ph = xq[((size_t)t * 64 + lane) * 2], pl = xq[((size_t)t * 64 + lane) * 2 + 1];
;       const int idA = idxg[(size_t)t * 128 + lane], idB = idxg[(size_t)t * 128 + 64 + lane];
;       unsigned long long m0 = __ballot((idA >> 12) == r), m1 = __ballot((idB >> 12) == r);
;       while (m0 | m1) {
;         int jk[16];
;         u32x4 rw[16];
;         const int nvalid = min((int)(__popcll(m0) + __popcll(m1)), 16);
;         int jfirst, efirst;
;         if (m0) { jfirst = __builtin_amdgcn_readfirstlane(__ffsll((long long)m0) - 1); efirst = __builtin_amdgcn_readlane(idA, jfirst); }
;         else { const int j1 = __builtin_amdgcn_readfirstlane(__ffsll((long long)m1) - 1); efirst = __builtin_amdgcn_readlane(idB, j1); jfirst = 64 + j1; }
; #pragma unroll
;         for (int k = 0; k < 16; ++k) {
;           int j = jfirst, e = efirst;
;           if (m0) { const int jj = __builtin_amdgcn_readfirstlane(__ffsll((long long)m0) - 1); m0 &= m0 - 1ull; j = jj; e = __builtin_amdgcn_readlane(idA, jj); }
;           else if (m1) { const int jj = __builtin_amdgcn_readfirstlane(__ffsll((long long)m1) - 1); m1 &= m1 - 1ull; j = 64 + jj; e = __builtin_amdgcn_readlane(idB, jj); }
;           jk[k] = j;
;           rw[k] = *(const u32x4*)(ub + (size_t)e * 1024 + lane * 16);
;         }
; #pragma unroll
;         for (int bt = 0; bt < 2; ++bt) {
;           int dv[8];
; #pragma unroll
;           for (int k = 0; k < 8; ++k) {
;             int dh = 0, dl = 0;
; #pragma unroll
;             for (int q = 0; q < 4; ++q) {
;               dh = __builtin_amdgcn_sdot8((int)rw[bt * 8 + k][q], (int)ph[q], dh, false);
;               dl = __builtin_amdgcn_sdot8((int)rw[bt * 8 + k][q], (int)pl[q], dl, false);
;             }
;             dv[k] = 16 * dh + dl;
;           }
;           int a4[4], a2[2];
; #pragma unroll
;           for (int k = 0; k < 4; ++k) {
;             const int mine = b5 ? dv[k + 4] : dv[k], oth = b5 ? dv[k] : dv[k + 4];
;             a4[k] = mine + __shfl_xor(oth, 32);
;           }
; #pragma unroll
;           for (int k = 0; k < 2; ++k) {
;             const int mine = b4 ? a4[k + 2] : a4[k], oth = b4 ? a4[k] : a4[k + 2];
;             a2[k] = mine + __shfl_xor(oth, 16);
;           }
;           int c1;
;           {
.Lgu_segA:
	v_lshrrev_b32_e32 v103, 12, v94
	v_lshrrev_b32_e32 v104, 12, v95
	v_cmp_eq_u32_e64 s[44:45], s33, v103
	v_cmp_eq_u32_e64 s[42:43], s33, v104
	s_nop 3
	s_bcnt1_i32_b64 s59, s[44:45]
	s_bcnt1_i32_b64 s56, s[42:43]
	s_add_i32 s56, s56, s59
	s_cmp_eq_u32 s56, 0
	s_cbranch_scc1 .Lgu_tnext
	v_mbcnt_lo_u32_b32 v114, s44, 0
	v_mbcnt_hi_u32_b32 v114, s45, v114
	v_mbcnt_lo_u32_b32 v111, s42, 0
	v_mbcnt_hi_u32_b32 v111, s43, v111
	v_lshl_add_u32 v113, v94, 10, v98
	v_lshl_add_u32 v100, v114, 2, s60
	v_add_u32_e32 v111, s59, v111
	s_mov_b64 exec, s[44:45]
	ds_write_b32 v100, v113
	s_mov_b64 exec, -1
	v_add_u32_e32 v113, 0x100, v98
	v_lshl_add_u32 v100, v111, 2, s60
	v_lshl_add_u32 v113, v95, 10, v113
	s_mov_b64 exec, s[42:43]
	ds_write_b32 v100, v113
	s_mov_b64 exec, -1
	s_add_i32 s57, s56, 3
	s_lshr_b32 s57, s57, 2
	v_lshl_add_u32 v101, v99, 2, s60
	v_mov_b32_e32 v102, v99
	s_mov_b32 s58, 0
	ds_read_b32 v115, v101
	v_add_u32_e32 v101, 16, v101
	s_waitcnt lgkmcnt(0)
	ds_read_b32 v116, v101
	v_cmp_gt_u32_e64 s[50:51], s56, v102
	v_add_u32_e32 v101, 16, v101
	v_add_u32_e32 v102, 4, v102
	s_nop 0
	v_cndmask_b32_e64 v103, 0, v115, s[50:51]
	v_and_or_b32 v104, v103, s67, v96
	v_and_b32_e32 v105, 0x3ff, v103
	s_and_b64 s[50:51], s[50:51], s[8:9]
	global_load_dwordx4 v[32:35], v104, s[34:35]
	global_load_dwordx4 v[36:39], v104, s[34:35] offset:256
	global_load_dwordx4 v[40:43], v104, s[34:35] offset:512
	global_load_dwordx4 v[44:47], v104, s[34:35] offset:768
	s_waitcnt lgkmcnt(0)
	ds_read_b32 v117, v101
	v_cmp_gt_u32_e64 s[52:53], s56, v102
	v_add_u32_e32 v101, 16, v101
	v_add_u32_e32 v102, 4, v102
	s_nop 0
	v_cndmask_b32_e64 v103, 0, v116, s[52:53]
	v_and_or_b32 v104, v103, s67, v96
	v_and_b32_e32 v106, 0x3ff, v103
	s_and_b64 s[52:53], s[52:53], s[8:9]
	global_load_dwordx4 v[48:51], v104, s[34:35]
	global_load_dwordx4 v[52:55], v104, s[34:35] offset:256
	global_load_dwordx4 v[56:59], v104, s[34:35] offset:512
	global_load_dwordx4 v[60:63], v104, s[34:35] offset:768
.Lgu_gloopA:
	s_waitcnt lgkmcnt(0)
	ds_read_b32 v115, v101
	v_cmp_gt_u32_e64 s[54:55], s56, v102
	v_add_u32_e32 v101, 16, v101
	v_add_u32_e32 v102, 4, v102
	s_nop 0
	v_cndmask_b32_e64 v103, 0, v117, s[54:55]
	v_and_or_b32 v104, v103, s67, v96
	v_and_b32_e32 v107, 0x3ff, v103
	s_and_b64 s[54:55], s[54:55], s[8:9]
	global_load_dwordx4 v[144:147], v104, s[34:35]
	global_load_dwordx4 v[148:151], v104, s[34:35] offset:256
	global_load_dwordx4 v[152:155], v104, s[34:35] offset:512
	global_load_dwordx4 v[156:159], v104, s[34:35] offset:768
	s_waitcnt vmcnt(8)
	v_mov_b32_e32 v108, 0
	v_mov_b32_e32 v109, 0
	s_nop 1
	v_dot8c_i32_i4_e32 v108, v32, v168
	v_dot8c_i32_i4_e32 v109, v32, v172
	v_dot8c_i32_i4_e32 v108, v33, v169
	v_dot8c_i32_i4_e32 v109, v33, v173
	v_dot8c_i32_i4_e32 v108, v34, v170
	v_dot8c_i32_i4_e32 v109, v34, v174
	v_dot8c_i32_i4_e32 v108, v35, v171
	v_dot8c_i32_i4_e32 v109, v35, v175
	v_dot8c_i32_i4_e32 v108, v36, v176
	v_dot8c_i32_i4_e32 v109, v36, v180
	v_dot8c_i32_i4_e32 v108, v37, v177
	v_dot8c_i32_i4_e32 v109, v37, v181
	v_dot8c_i32_i4_e32 v108, v38, v178
	v_dot8c_i32_i4_e32 v109, v38, v182
	v_dot8c_i32_i4_e32 v108, v39, v179
	v_dot8c_i32_i4_e32 v109, v39, v183
	v_dot8c_i32_i4_e32 v108, v40, v184
	v_dot8c_i32_i4_e32 v109, v40, v188
	v_dot8c_i32_i4_e32 v108, v41, v185
	v_dot8c_i32_i4_e32 v109, v41, v189
	v_dot8c_i32_i4_e32 v108, v42, v186
	v_dot8c_i32_i4_e32 v109, v42, v190
	v_dot8c_i32_i4_e32 v108, v43, v187
	v_dot8c_i32_i4_e32 v109, v43, v191
	v_dot8c_i32_i4_e32 v108, v44, v192
	v_dot8c_i32_i4_e32 v109, v44, v196
	v_dot8c_i32_i4_e32 v108, v45, v193
	v_dot8c_i32_i4_e32 v109, v45, v197
	v_dot8c_i32_i4_e32 v108, v46, v194
	v_dot8c_i32_i4_e32 v109, v46, v198
	v_dot8c_i32_i4_e32 v108, v47, v195
	v_dot8c_i32_i4_e32 v109, v47, v199
	s_nop 2
	v_lshl_add_u32 v110, v108, 4, v109
	s_nop 1
	v_add_u32_dpp v110, v110, v110 quad_perm:[1,0,3,2] row_mask:0xf bank_mask:0xf
	s_nop 1
	v_add_u32_dpp v110, v110, v110 quad_perm:[2,3,0,1] row_mask:0xf bank_mask:0xf
	s_nop 1
	v_add_u32_dpp v110, v110, v110 row_half_mirror row_mask:0xf bank_mask:0xf
	s_nop 1
	v_add_u32_dpp v110, v110, v110 row_mirror row_mask:0xf bank_mask:0xf
	s_mov_b64 exec, s[50:51]
	global_store_dword v105, v110, s[48:49]
	s_mov_b64 exec, -1
	s_add_i32 s58, s58, 1
	s_cmp_ge_u32 s58, s57
	s_cbranch_scc1 .Lgu_tnext
	s_waitcnt lgkmcnt(0)
	ds_read_b32 v116, v101
	v_cmp_gt_u32_e64 s[50:51], s56, v102
	v_add_u32_e32 v101, 16, v101
	v_add_u32_e32 v102, 4, v102
	s_nop 0
	v_cndmask_b32_e64 v103, 0, v115, s[50:51]
	v_and_or_b32 v104, v103, s67, v96
	v_and_b32_e32 v105, 0x3ff, v103
	s_and_b64 s[50:51], s[50:51], s[8:9]
	global_load_dwordx4 v[32:35], v104, s[34:35]
	global_load_dwordx4 v[36:39], v104, s[34:35] offset:256
	global_load_dwordx4 v[40:43], v104, s[34:35] offset:512
	global_load_dwordx4 v[44:47], v104, s[34:35] offset:768
	s_waitcnt vmcnt(8)
	v_mov_b32_e32 v108, 0
	v_mov_b32_e32 v109, 0
	s_nop 1
	v_dot8c_i32_i4_e32 v108, v48, v168
	v_dot8c_i32_i4_e32 v109, v48, v172
	v_dot8c_i32_i4_e32 v108, v49, v169
	v_dot8c_i32_i4_e32 v109, v49, v173
	v_dot8c_i32_i4_e32 v108, v50, v170
	v_dot8c_i32_i4_e32 v109, v50, v174
	v_dot8c_i32_i4_e32 v108, v51, v171
	v_dot8c_i32_i4_e32 v109, v51, v175
	v_dot8c_i32_i4_e32 v108, v52, v176
	v_dot8c_i32_i4_e32 v109, v52, v180
	v_dot8c_i32_i4_e32 v108, v53, v177
	v_dot8c_i32_i4_e32 v109, v53, v181
	v_dot8c_i32_i4_e32 v108, v54, v178
	v_dot8c_i32_i4_e32 v109, v54, v182
	v_dot8c_i32_i4_e32 v108, v55, v179
	v_dot8c_i32_i4_e32 v109, v55, v183
	v_dot8c_i32_i4_e32 v108, v56, v184
	v_dot8c_i32_i4_e32 v109, v56, v188
	v_dot8c_i32_i4_e32 v108, v57, v185
	v_dot8c_i32_i4_e32 v109, v57, v189
	v_dot8c_i32_i4_e32 v108, v58, v186
	v_dot8c_i32_i4_e32 v109, v58, v190
	v_dot8c_i32_i4_e32 v108, v59, v187
	v_dot8c_i32_i4_e32 v109, v59, v191
	v_dot8c_i32_i4_e32 v108, v60, v192
	v_dot8c_i32_i4_e32 v109, v60, v196
	v_dot8c_i32_i4_e32 v108, v61, v193
	v_dot8c_i32_i4_e32 v109, v61, v197
	v_dot8c_i32_i4_e32 v108, v62, v194
	v_dot8c_i32_i4_e32 v109, v62, v198
	v_dot8c_i32_i4_e32 v108, v63, v195
	v_dot8c_i32_i4_e32 v109, v63, v199
	s_nop 2
	v_lshl_add_u32 v110, v108, 4, v109
	s_nop 1
	v_add_u32_dpp v110, v110, v110 quad_perm:[1,0,3,2] row_mask:0xf bank_mask:0xf
	s_nop 1
	v_add_u32_dpp v110, v110, v110 quad_perm:[2,3,0,1] row_mask:0xf bank_mask:0xf
	s_nop 1
	v_add_u32_dpp v110, v110, v110 row_half_mirror row_mask:0xf bank_mask:0xf
	s_nop 1
	v_add_u32_dpp v110, v110, v110 row_mirror row_mask:0xf bank_mask:0xf
	s_mov_b64 exec, s[52:53]
	global_store_dword v106, v110, s[48:49]
	s_mov_b64 exec, -1
	s_add_i32 s58, s58, 1
	s_cmp_ge_u32 s58, s57
	s_cbranch_scc1 .Lgu_tnext
; __device__ void phase_gather_u(const Params& p) {
;     ...
;     for (int t = tbase; t < T_TOK; t += tstride) {
;       const u32x4 ph = xq[((size_t)t * 64 + lane) * 2], pl = xq[((size_t)t * 64 + lane) * 2 + 1];
;       const int idA = idxg[(size_t)t * 128 + lane], idB = idxg[(size_t)t * 128 + 64 + lane];
;       unsigned long long m0 = __ballot((idA >> 12) == r), m1 = __ballot((idB >> 12) == r);
;       while (m0 | m1) {
;         int jk[16];
;         u32x4 rw[16];
;         const int nvalid = min((int)(__popcll(m0) + __popcll(m1)), 16);
;         int jfirst, efirst;
;         if (m0) { jfirst = __builtin_amdgcn_readfirstlane(__ffsll((long long)m0) - 1); efirst = __builtin_amdgcn_readlane(idA, jfirst); }
;         else { const int j1 = __builtin_amdgcn_readfirstlane(__ffsll((long long)m1) - 1); efirst = __builtin_amdgcn_readlane(idB, j1); jfirst = 64 + j1; }
; #pragma unroll
;     ...
; #pragma unroll
;         for (int bt = 0; bt < 2; ++bt) {
;           int dv[8];
; #pragma unroll
;           for (int k = 0; k < 8; ++k) {
;             int dh = 0, dl = 0;
; #pragma unroll
;             for (int q = 0; q < 4; ++q) {
;               dh = __builtin_amdgcn_sdot8((int)rw[bt * 8 + k][q], (int)ph[q], dh, false);
;               dl = __builtin_amdgcn_sdot8((int)rw[bt * 8 + k][q], (int)pl[q], dl, false);
;             }
;             dv[k] = 16 * dh + dl;
;           }
;           int a4[4], a2[2];
; #pragma unroll
;           for (int k = 0; k < 4; ++k) {
;             const int mine = b5 ? dv[k + 4] : dv[k], oth = b5 ? dv[k] : dv[k + 4];
;             a4[k] = mine + __shfl_xor(oth, 32);
;           }
; #pragma unroll
;           for (int k = 0; k < 2; ++k) {
;             const int mine = b4 ? a4[k + 2] : a4[k], oth = b4 ? a4[k] : a4[k + 2];
;             a2[k] = mine + __shfl_xor(oth, 16);
;           }
;           int c1;
;           {
;             const int mine = b3 ? a2[1] : a2[0], oth = b3 ? a2[0] : a2[1];
;             c1 = mine + __shfl_xor(oth, 8);
;           }
;           c1 += __shfl_xor(c1, 4);
;           c1 += __shfl_xor(c1, 2);
;           c1 += __shfl_xor(c1, 1);
;           const int val = __shfl(c1, srcl);
;           int jsel = jk[bt * 8];
; #pragma unroll
;           for (int k = 1; k < 8; ++k) jsel = (lane == k) ? jk[bt * 8 + k] : jsel;
;           if (lane < 8 && lane < nvalid - bt * 8) wbuf[(size_t)t * 128 + jsel] = val;
	s_waitcnt lgkmcnt(0)
	ds_read_b32 v117, v101
	v_cmp_gt_u32_e64 s[52:53], s56, v102
	v_add_u32_e32 v101, 16, v101
	v_add_u32_e32 v102, 4, v102
	s_nop 0
	v_cndmask_b32_e64 v103, 0, v116, s[52:53]
	v_and_or_b32 v104, v103, s67, v96
	v_and_b32_e32 v106, 0x3ff, v103
	s_and_b64 s[52:53], s[52:53], s[8:9]
	global_load_dwordx4 v[48:51], v104, s[34:35]
	global_load_dwordx4 v[52:55], v104, s[34:35] offset:256
	global_load_dwordx4 v[56:59], v104, s[34:35] offset:512
	global_load_dwordx4 v[60:63], v104, s[34:35] offset:768
	s_waitcnt vmcnt(8)
	v_mov_b32_e32 v108, 0
	v_mov_b32_e32 v109, 0
	s_nop 1
	v_dot8c_i32_i4_e32 v108, v144, v168
	v_dot8c_i32_i4_e32 v109, v144, v172
	v_dot8c_i32_i4_e32 v108, v145, v169
	v_dot8c_i32_i4_e32 v109, v145, v173
	v_dot8c_i32_i4_e32 v108, v146, v170
	v_dot8c_i32_i4_e32 v109, v146, v174
	v_dot8c_i32_i4_e32 v108, v147, v171
	v_dot8c_i32_i4_e32 v109, v147, v175
	v_dot8c_i32_i4_e32 v108, v148, v176
	v_dot8c_i32_i4_e32 v109, v148, v180
	v_dot8c_i32_i4_e32 v108, v149, v177
	v_dot8c_i32_i4_e32 v109, v149, v181
	v_dot8c_i32_i4_e32 v108, v150, v178
	v_dot8c_i32_i4_e32 v109, v150, v182
	v_dot8c_i32_i4_e32 v108, v151, v179
	v_dot8c_i32_i4_e32 v109, v151, v183
	v_dot8c_i32_i4_e32 v108, v152, v184
	v_dot8c_i32_i4_e32 v109, v152, v188
	v_dot8c_i32_i4_e32 v108, v153, v185
	v_dot8c_i32_i4_e32 v109, v153, v189
	v_dot8c_i32_i4_e32 v108, v154, v186
	v_dot8c_i32_i4_e32 v109, v154, v190
	v_dot8c_i32_i4_e32 v108, v155, v187
	v_dot8c_i32_i4_e32 v109, v155, v191
	v_dot8c_i32_i4_e32 v108, v156, v192
	v_dot8c_i32_i4_e32 v109, v156, v196
	v_dot8c_i32_i4_e32 v108, v157, v193
	v_dot8c_i32_i4_e32 v109, v157, v197
	v_dot8c_i32_i4_e32 v108, v158, v194
	v_dot8c_i32_i4_e32 v109, v158, v198
	v_dot8c_i32_i4_e32 v108, v159, v195
	v_dot8c_i32_i4_e32 v109, v159, v199
	s_nop 2
	v_lshl_add_u32 v110, v108, 4, v109
	s_nop 1
	v_add_u32_dpp v110, v110, v110 quad_perm:[1,0,3,2] row_mask:0xf bank_mask:0xf
	s_nop 1
	v_add_u32_dpp v110, v110, v110 quad_perm:[2,3,0,1] row_mask:0xf bank_mask:0xf
	s_nop 1
	v_add_u32_dpp v110, v110, v110 row_half_mirror row_mask:0xf bank_mask:0xf
	s_nop 1
	v_add_u32_dpp v110, v110, v110 row_mirror row_mask:0xf bank_mask:0xf
	s_mov_b64 exec, s[54:55]
	global_store_dword v107, v110, s[48:49]
	s_mov_b64 exec, -1
	s_add_i32 s58, s58, 1
	s_cmp_lt_u32 s58, s57
	s_cbranch_scc1 .Lgu_gloopA
	s_branch .Lgu_tnext
.Lgu_segB:
	v_lshrrev_b32_e32 v103, 12, v232
	v_lshrrev_b32_e32 v104, 12, v233
	v_cmp_eq_u32_e64 s[44:45], s33, v103
	v_cmp_eq_u32_e64 s[42:43], s33, v104
	s_nop 3
	s_bcnt1_i32_b64 s59, s[44:45]
	s_bcnt1_i32_b64 s56, s[42:43]
	s_add_i32 s56, s56, s59
	s_cmp_eq_u32 s56, 0
	s_cbranch_scc1 .Lgu_tnext
	v_mbcnt_lo_u32_b32 v114, s44, 0
	v_mbcnt_hi_u32_b32 v114, s45, v114
	v_mbcnt_lo_u32_b32 v111, s42, 0
	v_mbcnt_hi_u32_b32 v111, s43, v111
	v_lshl_add_u32 v113, v232, 10, v98
	v_lshl_add_u32 v100, v114, 2, s60
	v_add_u32_e32 v111, s59, v111
	s_mov_b64 exec, s[44:45]
	ds_write_b32 v100, v113
	s_mov_b64 exec, -1
	v_add_u32_e32 v113, 0x100, v98
	v_lshl_add_u32 v100, v111, 2, s60
	v_lshl_add_u32 v113, v233, 10, v113
	s_mov_b64 exec, s[42:43]
	ds_write_b32 v100, v113
	s_mov_b64 exec, -1
	s_add_i32 s57, s56, 3
	s_lshr_b32 s57, s57, 2
	v_lshl_add_u32 v101, v99, 2, s60
	v_mov_b32_e32 v102, v99
	s_mov_b32 s58, 0
	ds_read_b32 v115, v101
	v_add_u32_e32 v101, 16, v101
	s_waitcnt lgkmcnt(0)
	ds_read_b32 v116, v101
	v_cmp_gt_u32_e64 s[50:51], s56, v102
	v_add_u32_e32 v101, 16, v101
	v_add_u32_e32 v102, 4, v102
	s_nop 0
	v_cndmask_b32_e64 v103, 0, v115, s[50:51]
	v_and_or_b32 v104, v103, s67, v96
	v_and_b32_e32 v105, 0x3ff, v103
	s_and_b64 s[50:51], s[50:51], s[8:9]
	global_load_dwordx4 v[32:35], v104, s[34:35]
	global_load_dwordx4 v[36:39], v104, s[34:35] offset:256
	global_load_dwordx4 v[40:43], v104, s[34:35] offset:512
	global_load_dwordx4 v[44:47], v104, s[34:35] offset:768
	s_waitcnt lgkmcnt(0)
	ds_read_b32 v117, v101
	v_cmp_gt_u32_e64 s[52:53], s56, v102
	v_add_u32_e32 v101, 16, v101
	v_add_u32_e32 v102, 4, v102
	s_nop 0
	v_cndmask_b32_e64 v103, 0, v116, s[52:53]
	v_and_or_b32 v104, v103, s67, v96
	v_and_b32_e32 v106, 0x3ff, v103
	s_and_b64 s[52:53], s[52:53], s[8:9]
	global_load_dwordx4 v[48:51], v104, s[34:35]
	global_load_dwordx4 v[52:55], v104, s[34:35] offset:256
	global_load_dwordx4 v[56:59], v104, s[34:35] offset:512
	global_load_dwordx4 v[60:63], v104, s[34:35] offset:768
; __device__ void phase_gather_u(const Params& p) {
;     ...
; #pragma unroll
;         for (int k = 0; k < 16; ++k) {
;           int j = jfirst, e = efirst;
;           if (m0) { const int jj = __builtin_amdgcn_readfirstlane(__ffsll((long long)m0) - 1); m0 &= m0 - 1ull; j = jj; e = __builtin_amdgcn_readlane(idA, jj); }
;           else if (m1) { const int jj = __builtin_amdgcn_readfirstlane(__ffsll((long long)m1) - 1); m1 &= m1 - 1ull; j = 64 + jj; e = __builtin_amdgcn_readlane(idB, jj); }
;           jk[k] = j;
;           rw[k] = *(const u32x4*)(ub + (size_t)e * 1024 + lane * 16);
;         }
; #pragma unroll
;         for (int bt = 0; bt < 2; ++bt) {
;           int dv[8];
; #pragma unroll
;           for (int k = 0; k < 8; ++k) {
;             int dh = 0, dl = 0;
; #pragma unroll
;             for (int q = 0; q < 4; ++q) {
;               dh = __builtin_amdgcn_sdot8((int)rw[bt * 8 + k][q], (int)ph[q], dh, false);
;               dl = __builtin_amdgcn_sdot8((int)rw[bt * 8 + k][q], (int)pl[q], dl, false);
;             }
;             dv[k] = 16 * dh + dl;
;           }
;           int a4[4], a2[2];
; #pragma unroll
;           for (int k = 0; k < 4; ++k) {
;             const int mine = b5 ? dv[k + 4] : dv[k], oth = b5 ? dv[k] : dv[k + 4];
;             a4[k] = mine + __shfl_xor(oth, 32);
;           }
; #pragma unroll
;           for (int k = 0; k < 2; ++k) {
;             const int mine = b4 ? a4[k + 2] : a4[k], oth = b4 ? a4[k] : a4[k + 2];
;             a2[k] = mine + __shfl_xor(oth, 16);
;           }
;           int c1;
;           {
;             const int mine = b3 ? a2[1] : a2[0], oth = b3 ? a2[0] : a2[1];
;             c1 = mine + __shfl_xor(oth, 8);
;           }
;           c1 += __shfl_xor(c1, 4);
;           c1 += __shfl_xor(c1, 2);
;           c1 += __shfl_xor(c1, 1);
;           const int val = __shfl(c1, srcl);
;           int jsel = jk[bt * 8];
; #pragma unroll
;           for (int k = 1; k < 8; ++k) jsel = (lane == k) ? jk[bt * 8 + k] : jsel;
;           if (lane < 8 && lane < nvalid - bt * 8) wbuf[(size_t)t * 128 + jsel] = val;
.Lgu_gloopB:
	s_waitcnt lgkmcnt(0)
	ds_read_b32 v115, v101
	v_cmp_gt_u32_e64 s[54:55], s56, v102
	v_add_u32_e32 v101, 16, v101
	v_add_u32_e32 v102, 4, v102
	s_nop 0
	v_cndmask_b32_e64 v103, 0, v117, s[54:55]
	v_and_or_b32 v104, v103, s67, v96
	v_and_b32_e32 v107, 0x3ff, v103
	s_and_b64 s[54:55], s[54:55], s[8:9]
	global_load_dwordx4 v[144:147], v104, s[34:35]
	global_load_dwordx4 v[148:151], v104, s[34:35] offset:256
	global_load_dwordx4 v[152:155], v104, s[34:35] offset:512
	global_load_dwordx4 v[156:159], v104, s[34:35] offset:768
	s_waitcnt vmcnt(8)
	v_mov_b32_e32 v108, 0
	v_mov_b32_e32 v109, 0
	s_nop 1
	v_dot8c_i32_i4_e32 v108, v32, v200
	v_dot8c_i32_i4_e32 v109, v32, v204
	v_dot8c_i32_i4_e32 v108, v33, v201
	v_dot8c_i32_i4_e32 v109, v33, v205
	v_dot8c_i32_i4_e32 v108, v34, v202
	v_dot8c_i32_i4_e32 v109, v34, v206
	v_dot8c_i32_i4_e32 v108, v35, v203
	v_dot8c_i32_i4_e32 v109, v35, v207
	v_dot8c_i32_i4_e32 v108, v36, v208
	v_dot8c_i32_i4_e32 v109, v36, v212
	v_dot8c_i32_i4_e32 v108, v37, v209
	v_dot8c_i32_i4_e32 v109, v37, v213
	v_dot8c_i32_i4_e32 v108, v38, v210
	v_dot8c_i32_i4_e32 v109, v38, v214
	v_dot8c_i32_i4_e32 v108, v39, v211
	v_dot8c_i32_i4_e32 v109, v39, v215
	v_dot8c_i32_i4_e32 v108, v40, v216
	v_dot8c_i32_i4_e32 v109, v40, v220
	v_dot8c_i32_i4_e32 v108, v41, v217
	v_dot8c_i32_i4_e32 v109, v41, v221
	v_dot8c_i32_i4_e32 v108, v42, v218
	v_dot8c_i32_i4_e32 v109, v42, v222
	v_dot8c_i32_i4_e32 v108, v43, v219
	v_dot8c_i32_i4_e32 v109, v43, v223
	v_dot8c_i32_i4_e32 v108, v44, v224
	v_dot8c_i32_i4_e32 v109, v44, v228
	v_dot8c_i32_i4_e32 v108, v45, v225
	v_dot8c_i32_i4_e32 v109, v45, v229
	v_dot8c_i32_i4_e32 v108, v46, v226
	v_dot8c_i32_i4_e32 v109, v46, v230
	v_dot8c_i32_i4_e32 v108, v47, v227
	v_dot8c_i32_i4_e32 v109, v47, v231
	s_nop 2
	v_lshl_add_u32 v110, v108, 4, v109
	s_nop 1
	v_add_u32_dpp v110, v110, v110 quad_perm:[1,0,3,2] row_mask:0xf bank_mask:0xf
	s_nop 1
	v_add_u32_dpp v110, v110, v110 quad_perm:[2,3,0,1] row_mask:0xf bank_mask:0xf
	s_nop 1
	v_add_u32_dpp v110, v110, v110 row_half_mirror row_mask:0xf bank_mask:0xf
	s_nop 1
	v_add_u32_dpp v110, v110, v110 row_mirror row_mask:0xf bank_mask:0xf
	s_mov_b64 exec, s[50:51]
	global_store_dword v105, v110, s[48:49]
	s_mov_b64 exec, -1
	s_add_i32 s58, s58, 1
	s_cmp_ge_u32 s58, s57
	s_cbranch_scc1 .Lgu_tnext
	s_waitcnt lgkmcnt(0)
	ds_read_b32 v116, v101
	v_cmp_gt_u32_e64 s[50:51], s56, v102
	v_add_u32_e32 v101, 16, v101
	v_add_u32_e32 v102, 4, v102
	s_nop 0
	v_cndmask_b32_e64 v103, 0, v115, s[50:51]
	v_and_or_b32 v104, v103, s67, v96
	v_and_b32_e32 v105, 0x3ff, v103
	s_and_b64 s[50:51], s[50:51], s[8:9]
	global_load_dwordx4 v[32:35], v104, s[34:35]
	global_load_dwordx4 v[36:39], v104, s[34:35] offset:256
	global_load_dwordx4 v[40:43], v104, s[34:35] offset:512
	global_load_dwordx4 v[44:47], v104, s[34:35] offset:768
	s_waitcnt vmcnt(8)
	v_mov_b32_e32 v108, 0
	v_mov_b32_e32 v109, 0
	s_nop 1
	v_dot8c_i32_i4_e32 v108, v48, v200
	v_dot8c_i32_i4_e32 v109, v48, v204
	v_dot8c_i32_i4_e32 v108, v49, v201
	v_dot8c_i32_i4_e32 v109, v49, v205
	v_dot8c_i32_i4_e32 v108, v50, v202
	v_dot8c_i32_i4_e32 v109, v50, v206
	v_dot8c_i32_i4_e32 v108, v51, v203
	v_dot8c_i32_i4_e32 v109, v51, v207
	v_dot8c_i32_i4_e32 v108, v52, v208
	v_dot8c_i32_i4_e32 v109, v52, v212
	v_dot8c_i32_i4_e32 v108, v53, v209
	v_dot8c_i32_i4_e32 v109, v53, v213
	v_dot8c_i32_i4_e32 v108, v54, v210
	v_dot8c_i32_i4_e32 v109, v54, v214
	v_dot8c_i32_i4_e32 v108, v55, v211
	v_dot8c_i32_i4_e32 v109, v55, v215
	v_dot8c_i32_i4_e32 v108, v56, v216
	v_dot8c_i32_i4_e32 v109, v56, v220
	v_dot8c_i32_i4_e32 v108, v57, v217
	v_dot8c_i32_i4_e32 v109, v57, v221
	v_dot8c_i32_i4_e32 v108, v58, v218
	v_dot8c_i32_i4_e32 v109, v58, v222
	v_dot8c_i32_i4_e32 v108, v59, v219
	v_dot8c_i32_i4_e32 v109, v59, v223
	v_dot8c_i32_i4_e32 v108, v60, v224
	v_dot8c_i32_i4_e32 v109, v60, v228
	v_dot8c_i32_i4_e32 v108, v61, v225
	v_dot8c_i32_i4_e32 v109, v61, v229
	v_dot8c_i32_i4_e32 v108, v62, v226
	v_dot8c_i32_i4_e32 v109, v62, v230
	v_dot8c_i32_i4_e32 v108, v63, v227
	v_dot8c_i32_i4_e32 v109, v63, v231
	s_nop 2
	v_lshl_add_u32 v110, v108, 4, v109
	s_nop 1
	v_add_u32_dpp v110, v110, v110 quad_perm:[1,0,3,2] row_mask:0xf bank_mask:0xf
	s_nop 1
	v_add_u32_dpp v110, v110, v110 quad_perm:[2,3,0,1] row_mask:0xf bank_mask:0xf
	s_nop 1
	v_add_u32_dpp v110, v110, v110 row_half_mirror row_mask:0xf bank_mask:0xf
	s_nop 1
	v_add_u32_dpp v110, v110, v110 row_mirror row_mask:0xf bank_mask:0xf
	s_mov_b64 exec, s[52:53]
	global_store_dword v106, v110, s[48:49]
	s_mov_b64 exec, -1
	s_add_i32 s58, s58, 1
	s_cmp_ge_u32 s58, s57
	s_cbranch_scc1 .Lgu_tnext
	s_waitcnt lgkmcnt(0)
	ds_read_b32 v117, v101
	v_cmp_gt_u32_e64 s[52:53], s56, v102
	v_add_u32_e32 v101, 16, v101
	v_add_u32_e32 v102, 4, v102
	s_nop 0
	v_cndmask_b32_e64 v103, 0, v116, s[52:53]
	v_and_or_b32 v104, v103, s67, v96
	v_and_b32_e32 v106, 0x3ff, v103
	s_and_b64 s[52:53], s[52:53], s[8:9]
	global_load_dwordx4 v[48:51], v104, s[34:35]
	global_load_dwordx4 v[52:55], v104, s[34:35] offset:256
	global_load_dwordx4 v[56:59], v104, s[34:35] offset:512
	global_load_dwordx4 v[60:63], v104, s[34:35] offset:768
	s_waitcnt vmcnt(8)
	v_mov_b32_e32 v108, 0
	v_mov_b32_e32 v109, 0
	s_nop 1
	v_dot8c_i32_i4_e32 v108, v144, v200
	v_dot8c_i32_i4_e32 v109, v144, v204
	v_dot8c_i32_i4_e32 v108, v145, v201
	v_dot8c_i32_i4_e32 v109, v145, v205
	v_dot8c_i32_i4_e32 v108, v146, v202
	v_dot8c_i32_i4_e32 v109, v146, v206
	v_dot8c_i32_i4_e32 v108, v147, v203
	v_dot8c_i32_i4_e32 v109, v147, v207
	v_dot8c_i32_i4_e32 v108, v148, v208
	v_dot8c_i32_i4_e32 v109, v148, v212
	v_dot8c_i32_i4_e32 v108, v149, v209
	v_dot8c_i32_i4_e32 v109, v149, v213
	v_dot8c_i32_i4_e32 v108, v150, v210
	v_dot8c_i32_i4_e32 v109, v150, v214
	v_dot8c_i32_i4_e32 v108, v151, v211
	v_dot8c_i32_i4_e32 v109, v151, v215
	v_dot8c_i32_i4_e32 v108, v152, v216
	v_dot8c_i32_i4_e32 v109, v152, v220
	v_dot8c_i32_i4_e32 v108, v153, v217
	v_dot8c_i32_i4_e32 v109, v153, v221
	v_dot8c_i32_i4_e32 v108, v154, v218
	v_dot8c_i32_i4_e32 v109, v154, v222
	v_dot8c_i32_i4_e32 v108, v155, v219
	v_dot8c_i32_i4_e32 v109, v155, v223
	v_dot8c_i32_i4_e32 v108, v156, v224
	v_dot8c_i32_i4_e32 v109, v156, v228
	v_dot8c_i32_i4_e32 v108, v157, v225
	v_dot8c_i32_i4_e32 v109, v157, v229
	v_dot8c_i32_i4_e32 v108, v158, v226
	v_dot8c_i32_i4_e32 v109, v158, v230
	v_dot8c_i32_i4_e32 v108, v159, v227
	v_dot8c_i32_i4_e32 v109, v159, v231
	s_nop 2
	v_lshl_add_u32 v110, v108, 4, v109
	s_nop 1
	v_add_u32_dpp v110, v110, v110 quad_perm:[1,0,3,2] row_mask:0xf bank_mask:0xf
	s_nop 1
	v_add_u32_dpp v110, v110, v110 quad_perm:[2,3,0,1] row_mask:0xf bank_mask:0xf
	s_nop 1
	v_add_u32_dpp v110, v110, v110 row_half_mirror row_mask:0xf bank_mask:0xf
	s_nop 1
	v_add_u32_dpp v110, v110, v110 row_mirror row_mask:0xf bank_mask:0xf
	s_mov_b64 exec, s[54:55]
	global_store_dword v107, v110, s[48:49]
	s_mov_b64 exec, -1
	s_add_i32 s58, s58, 1
	s_cmp_lt_u32 s58, s57
	s_cbranch_scc1 .Lgu_gloopB
